# HGRN2 chunk loop: log(f) by v_log_f32 * ln2 instead of the denormal-scaled compensated expansion (16 sites, -144 instr per chunk-thread), on top of v24
# baseline (speedup 1.0000x reference)
; __device__ __forceinline__ float bflo(unsigned w) { return __uint_as_float(w << 16); }
; __device__ __forceinline__ float bfhi(unsigned w) { return __uint_as_float(w & 0xffff0000u); }
; __device__ __forceinline__ float sigmoidf_(float x) { return __builtin_amdgcn_rcpf(1.0f + __expf(-x)); }
; __device__ __forceinline__ float siluf_(float x) { return x * __builtin_amdgcn_rcpf(1.0f + __expf(-x)); }
; __device__ __forceinline__ void hg_mfma(Frame& F, bf16* Y, int u, unsigned* prog = nullptr) {
;     ...
;       float q0[8], q1[8], k0[8], k1[8], c0[8], c1[8];
;       { float a0 = 0.f, a1 = 0.f;
; #pragma unroll
;         for (int i = 0; i < 8; ++i) { const float f0 = lb0 + (1.f - lb0) * sigmoidf_(bflo(fraw[i])), f1 = lb1 + (1.f - lb1) * sigmoidf_(bfhi(fraw[i]));
;           q0[i] = siluf_(bflo(qraw[i])); q1[i] = siluf_(bfhi(qraw[i])); k0[i] = 1.f - f0; k1[i] = 1.f - f1;
;           a0 += __logf(f0); a1 += __logf(f1); c0[i] = a0; c1[i] = a1; } }
.LBB0_1785:
	s_waitcnt vmcnt(16)
	v_and_b32_e32 v35, 0xffff0000, v115
	v_mul_f32_e32 v35, 0xbfb8aa3b, v35
	v_exp_f32_e32 v35, v35
	v_lshlrev_b32_e32 v34, 16, v115
	v_mul_f32_e32 v34, 0xbfb8aa3b, v34
	v_exp_f32_e32 v34, v34
	v_add_f32_e32 v35, 1.0, v35
	v_rcp_f32_e32 v42, v35
	v_lshlrev_b32_e32 v35, 16, v114
	v_mul_f32_e32 v36, 0xbfb8aa3b, v35
	v_exp_f32_e32 v36, v36
	v_add_f32_e32 v34, 1.0, v34
	v_rcp_f32_e32 v34, v34
	v_add_f32_e32 v36, 1.0, v36
	v_rcp_f32_e32 v36, v36
	s_nop 0
	v_mul_f32_e32 v80, v36, v35
	v_and_b32_e32 v35, 0xffff0000, v114
	v_mul_f32_e32 v36, 0xbfb8aa3b, v35
	v_exp_f32_e32 v36, v36
	s_nop 0
	v_add_f32_e32 v36, 1.0, v36
	v_rcp_f32_e32 v36, v36
	s_nop 0
	v_mul_f32_e32 v83, v36, v35
	s_waitcnt vmcnt(14)
	v_lshlrev_b32_e32 v35, 16, v117
	v_mul_f32_e32 v35, 0xbfb8aa3b, v35
	v_exp_f32_e32 v35, v35
	s_nop 0
	v_add_f32_e32 v35, 1.0, v35
	v_rcp_f32_e32 v36, v35
	v_and_b32_e32 v35, 0xffff0000, v117
	v_mul_f32_e32 v35, 0xbfb8aa3b, v35
	v_exp_f32_e32 v35, v35
	s_nop 0
	v_add_f32_e32 v35, 1.0, v35
	v_rcp_f32_e32 v44, v35
	v_lshlrev_b32_e32 v35, 16, v116
	v_mul_f32_e32 v37, 0xbfb8aa3b, v35
	v_exp_f32_e32 v37, v37
	s_nop 0
	v_add_f32_e32 v37, 1.0, v37
	v_rcp_f32_e32 v37, v37
	s_nop 0
	v_mul_f32_e32 v78, v37, v35
	v_and_b32_e32 v35, 0xffff0000, v116
	v_mul_f32_e32 v37, 0xbfb8aa3b, v35
	v_exp_f32_e32 v37, v37
	s_nop 0
	v_add_f32_e32 v37, 1.0, v37
	v_rcp_f32_e32 v37, v37
	s_nop 0
	v_mul_f32_e32 v81, v37, v35
	s_waitcnt vmcnt(12)
	v_and_b32_e32 v37, 0xffff0000, v119
	v_mul_f32_e32 v37, 0xbfb8aa3b, v37
	v_exp_f32_e32 v37, v37
	v_lshlrev_b32_e32 v35, 16, v119
	v_mul_f32_e32 v35, 0xbfb8aa3b, v35
	v_exp_f32_e32 v35, v35
	v_add_f32_e32 v37, 1.0, v37
	v_rcp_f32_e32 v43, v37
	v_lshlrev_b32_e32 v37, 16, v118
	v_mul_f32_e32 v38, 0xbfb8aa3b, v37
	v_exp_f32_e32 v38, v38
	v_add_f32_e32 v35, 1.0, v35
	v_rcp_f32_e32 v35, v35
	v_pk_fma_f32 v[42:43], v[102:103], v[42:43], v[98:99]
	v_add_f32_e32 v38, 1.0, v38
	v_rcp_f32_e32 v38, v38
	v_pk_fma_f32 v[34:35], v[100:101], v[34:35], v[104:105]
	v_mul_f32_e32 v79, v38, v37
	v_and_b32_e32 v37, 0xffff0000, v118
	v_mul_f32_e32 v38, 0xbfb8aa3b, v37
	v_exp_f32_e32 v38, v38
	v_cmp_gt_f32_e32 vcc, s54, v34
	v_add_f32_e32 v38, 1.0, v38
	v_rcp_f32_e32 v38, v38
	s_nop 0
	v_mul_f32_e32 v82, v38, v37
	s_waitcnt vmcnt(10)
	v_and_b32_e32 v38, 0xffff0000, v121
	v_mul_f32_e32 v38, 0xbfb8aa3b, v38
	v_exp_f32_e32 v38, v38
	v_lshlrev_b32_e32 v37, 16, v121
	v_mul_f32_e32 v37, 0xbfb8aa3b, v37
	v_exp_f32_e32 v37, v37
	v_add_f32_e32 v38, 1.0, v38
	v_rcp_f32_e32 v45, v38
	v_lshlrev_b32_e32 v38, 16, v120
	v_mul_f32_e32 v39, 0xbfb8aa3b, v38
	v_exp_f32_e32 v39, v39
	v_add_f32_e32 v37, 1.0, v37
	v_rcp_f32_e32 v37, v37
	v_pk_fma_f32 v[76:77], v[102:103], v[44:45], v[98:99]
	v_add_f32_e32 v39, 1.0, v39
	v_rcp_f32_e32 v39, v39
	v_pk_fma_f32 v[62:63], v[100:101], v[36:37], v[104:105]
	v_mul_f32_e32 v84, v39, v38
	v_and_b32_e32 v38, 0xffff0000, v120
	v_mul_f32_e32 v39, 0xbfb8aa3b, v38
	v_exp_f32_e32 v39, v39
	s_nop 0
	v_add_f32_e32 v39, 1.0, v39
	v_rcp_f32_e32 v39, v39
	s_nop 0
	v_mul_f32_e32 v87, v39, v38
	s_waitcnt vmcnt(8)
	v_and_b32_e32 v39, 0xffff0000, v130
	v_mul_f32_e32 v39, 0xbfb8aa3b, v39
	v_exp_f32_e32 v39, v39
	v_lshlrev_b32_e32 v38, 16, v130
	v_mul_f32_e32 v38, 0xbfb8aa3b, v38
	v_exp_f32_e32 v38, v38
	v_add_f32_e32 v39, 1.0, v39
	v_rcp_f32_e32 v46, v39
	v_lshlrev_b32_e32 v39, 16, v128
	v_mul_f32_e32 v40, 0xbfb8aa3b, v39
	v_exp_f32_e32 v40, v40
	v_add_f32_e32 v38, 1.0, v38
	v_rcp_f32_e32 v38, v38
	v_add_f32_e32 v40, 1.0, v40
	v_rcp_f32_e32 v40, v40
	s_nop 0
	v_mul_f32_e32 v88, v40, v39
	v_and_b32_e32 v39, 0xffff0000, v128
	v_mul_f32_e32 v40, 0xbfb8aa3b, v39
	v_exp_f32_e32 v40, v40
	s_nop 0
	v_add_f32_e32 v40, 1.0, v40
	v_rcp_f32_e32 v40, v40
	s_nop 0
	v_mul_f32_e32 v91, v40, v39
	s_waitcnt vmcnt(6)
	v_lshlrev_b32_e32 v39, 16, v134
	v_mul_f32_e32 v39, 0xbfb8aa3b, v39
	v_exp_f32_e32 v39, v39
	s_nop 0
	v_add_f32_e32 v39, 1.0, v39
	v_rcp_f32_e32 v58, v39
	v_and_b32_e32 v39, 0xffff0000, v134
	v_mul_f32_e32 v39, 0xbfb8aa3b, v39
	v_exp_f32_e32 v39, v39
	s_nop 0
	v_add_f32_e32 v39, 1.0, v39
	v_rcp_f32_e32 v48, v39
	v_lshlrev_b32_e32 v39, 16, v132
	v_mul_f32_e32 v40, 0xbfb8aa3b, v39
	v_exp_f32_e32 v40, v40
	s_nop 0
	v_add_f32_e32 v40, 1.0, v40
	v_rcp_f32_e32 v40, v40
	s_nop 0
	v_mul_f32_e32 v85, v40, v39
	v_and_b32_e32 v39, 0xffff0000, v132
	v_mul_f32_e32 v40, 0xbfb8aa3b, v39
	v_exp_f32_e32 v40, v40
	s_nop 0
	v_add_f32_e32 v40, 1.0, v40
	v_rcp_f32_e32 v40, v40
	s_nop 0
	v_mul_f32_e32 v89, v40, v39
	s_waitcnt vmcnt(4)
	v_and_b32_e32 v40, 0xffff0000, v138
	v_mul_f32_e32 v40, 0xbfb8aa3b, v40
	v_exp_f32_e32 v40, v40
	v_lshlrev_b32_e32 v39, 16, v138
	v_mul_f32_e32 v39, 0xbfb8aa3b, v39
	v_exp_f32_e32 v39, v39
	v_add_f32_e32 v40, 1.0, v40
	v_rcp_f32_e32 v47, v40
	v_lshlrev_b32_e32 v40, 16, v136
	v_mul_f32_e32 v41, 0xbfb8aa3b, v40
	v_exp_f32_e32 v41, v41
	v_add_f32_e32 v39, 1.0, v39
	v_rcp_f32_e32 v39, v39
	v_add_f32_e32 v41, 1.0, v41
	v_rcp_f32_e32 v41, v41
	s_nop 0
	v_mul_f32_e32 v86, v41, v40
	v_and_b32_e32 v40, 0xffff0000, v136
	v_mul_f32_e32 v41, 0xbfb8aa3b, v40
	v_exp_f32_e32 v41, v41
	s_nop 0
	v_add_f32_e32 v41, 1.0, v41
	v_rcp_f32_e32 v41, v41
	s_nop 0
	v_mul_f32_e32 v90, v41, v40
	s_waitcnt vmcnt(2)
; __device__ __forceinline__ float bflo(unsigned w) { return __uint_as_float(w << 16); }
; __device__ __forceinline__ float bfhi(unsigned w) { return __uint_as_float(w & 0xffff0000u); }
; __device__ __forceinline__ float sigmoidf_(float x) { return __builtin_amdgcn_rcpf(1.0f + __expf(-x)); }
; __device__ __forceinline__ float siluf_(float x) { return x * __builtin_amdgcn_rcpf(1.0f + __expf(-x)); }
; __device__ __forceinline__ int v_st(int k, int c) { const int kk = (k & ~0xC) | ((k & 4) << 1) | ((k & 8) >> 1); return ((kk >> 3) * 4 + (c >> 5)) * 512 + ((kk & 7) * 32 + (c & 31)) * 2; }
; __device__ __forceinline__ void hg_mfma(Frame& F, bf16* Y, int u, unsigned* prog = nullptr) {
;     ...
;         for (int i = 0; i < 8; ++i) { const float f0 = lb0 + (1.f - lb0) * sigmoidf_(bflo(fraw[i])), f1 = lb1 + (1.f - lb1) * sigmoidf_(bfhi(fraw[i]));
;           q0[i] = siluf_(bflo(qraw[i])); q1[i] = siluf_(bfhi(qraw[i])); k0[i] = 1.f - f0; k1[i] = 1.f - f1;
;           a0 += __logf(f0); a1 += __logf(f1); c0[i] = a0; c1[i] = a1; } }
;       { float* cs = (float*)(lds + HG_CS); cs[te * 128 + 2 * dp] = c0[7]; cs[te * 128 + 2 * dp + 1] = c1[7]; }
;       *(v4u*)(lds + HG_V + v_st(sr, sc)) = vs0; *(v4u*)(lds + HG_V + v_st(32 + sr, sc)) = vs1;
;       __syncthreads();
;       { const float* cs = (const float*)(lds + HG_CS); float off0 = 0.f, off1 = 0.f, tot0 = 0.f, tot1 = 0.f;
; #pragma unroll
;         for (int s = 0; s < 8; ++s) { const v2f x = *(const v2f*)(cs + s * 128 + 2 * dp); tot0 += x.x; tot1 += x.y; if (s < te) { off0 += x.x; off1 += x.y; } }
	v_lshlrev_b32_e32 v40, 16, v142
	v_mul_f32_e32 v40, 0xbfb8aa3b, v40
	v_exp_f32_e32 v40, v40
	s_nop 0
	v_add_f32_e32 v40, 1.0, v40
	v_rcp_f32_e32 v59, v40
	v_and_b32_e32 v40, 0xffff0000, v142
	v_mul_f32_e32 v40, 0xbfb8aa3b, v40
	v_exp_f32_e32 v40, v40
	v_pk_fma_f32 v[58:59], v[100:101], v[58:59], v[104:105]
	v_add_f32_e32 v40, 1.0, v40
	v_rcp_f32_e32 v49, v40
	v_lshlrev_b32_e32 v40, 16, v140
	v_mul_f32_e32 v41, 0xbfb8aa3b, v40
	v_exp_f32_e32 v41, v41
	v_pk_fma_f32 v[48:49], v[102:103], v[48:49], v[98:99]
	v_add_f32_e32 v41, 1.0, v41
	v_rcp_f32_e32 v41, v41
	s_nop 0
	v_mul_f32_e32 v92, v41, v40
	v_and_b32_e32 v40, 0xffff0000, v140
	v_mul_f32_e32 v41, 0xbfb8aa3b, v40
	v_exp_f32_e32 v41, v41
	s_nop 0
	v_add_f32_e32 v41, 1.0, v41
	v_rcp_f32_e32 v41, v41
	s_nop 0
	v_mul_f32_e32 v93, v41, v40
	v_log_f32_e32 v40, v34
	s_nop 0
	s_nop 1
	v_cmp_gt_f32_e32 vcc, s54, v62
	v_mul_f32_e32 v60, 0x3f317217, v40
	v_pk_add_f32 v[40:41], v[34:35], 1.0 op_sel_hi:[1,0] neg_lo:[1,0] neg_hi:[1,0]
	v_log_f32_e32 v36, v62
	s_nop 0
	s_nop 1
	v_cmp_gt_f32_e32 vcc, s54, v35
	v_mul_f32_e32 v64, 0x3f317217, v36
	v_pk_add_f32 v[36:37], v[62:63], 1.0 op_sel_hi:[1,0] neg_lo:[1,0] neg_hi:[1,0]
	v_log_f32_e32 v34, v35
	s_nop 0
	s_nop 1
	v_cmp_gt_f32_e32 vcc, s54, v63
	v_mul_f32_e32 v68, 0x3f317217, v34
	s_nop 0
	v_log_f32_e32 v34, v63
	s_nop 0
	s_nop 1
	v_mul_f32_e32 v74, 0x3f317217, v34
	v_pk_fma_f32 v[34:35], v[100:101], v[38:39], v[104:105]
	s_nop 0
	v_cmp_gt_f32_e32 vcc, s54, v34
	s_nop 1
	v_log_f32_e32 v38, v34
	s_nop 0
	s_nop 1
	v_cmp_gt_f32_e32 vcc, s54, v58
	v_mul_f32_e32 v62, 0x3f317217, v38
	s_nop 0
	v_log_f32_e32 v38, v58
	s_nop 0
	s_nop 1
	v_cmp_gt_f32_e32 vcc, s54, v35
	v_mul_f32_e32 v66, 0x3f317217, v38
	v_pk_add_f32 v[38:39], v[34:35], 1.0 op_sel_hi:[1,0] neg_lo:[1,0] neg_hi:[1,0]
	v_log_f32_e32 v34, v35
	s_nop 0
	s_nop 1
	v_cmp_gt_f32_e32 vcc, s54, v59
	v_mul_f32_e32 v70, 0x3f317217, v34
	v_pk_add_f32 v[34:35], v[58:59], 1.0 op_sel_hi:[1,0] neg_lo:[1,0] neg_hi:[1,0]
	v_log_f32_e32 v58, v59
	s_nop 0
	s_nop 1
	v_cmp_gt_f32_e32 vcc, s54, v42
	v_mul_f32_e32 v72, 0x3f317217, v58
	s_nop 0
	v_log_f32_e32 v58, v42
	s_nop 0
	s_nop 1
	v_cmp_gt_f32_e32 vcc, s54, v76
	v_mul_f32_e32 v61, 0x3f317217, v58
	v_pk_add_f32 v[58:59], v[42:43], 1.0 op_sel_hi:[1,0] neg_lo:[1,0] neg_hi:[1,0]
	v_log_f32_e32 v44, v76
	s_nop 0
	s_nop 1
	v_cmp_gt_f32_e32 vcc, s54, v43
	v_mul_f32_e32 v65, 0x3f317217, v44
	v_pk_add_f32 v[44:45], v[76:77], 1.0 op_sel_hi:[1,0] neg_lo:[1,0] neg_hi:[1,0]
	v_log_f32_e32 v42, v43
	s_nop 0
	s_nop 1
	v_cmp_gt_f32_e32 vcc, s54, v77
	v_mul_f32_e32 v69, 0x3f317217, v42
	s_nop 0
	v_log_f32_e32 v42, v77
	v_pk_add_f32 v[76:77], v[60:61], 0 op_sel_hi:[1,0]
	v_pk_add_f32 v[64:65], v[76:77], v[64:65]
	s_nop 0
	v_mul_f32_e32 v75, 0x3f317217, v42
	v_pk_fma_f32 v[42:43], v[102:103], v[46:47], v[98:99]
	v_pk_add_f32 v[68:69], v[64:65], v[68:69]
	v_cmp_gt_f32_e32 vcc, s54, v42
	v_pk_add_f32 v[60:61], v[68:69], v[74:75]
	s_nop 0
	v_log_f32_e32 v46, v42
	s_nop 0
	s_nop 1
	v_cmp_gt_f32_e32 vcc, s54, v48
	v_mul_f32_e32 v63, 0x3f317217, v46
	v_pk_add_f32 v[74:75], v[60:61], v[62:63]
	v_log_f32_e32 v46, v48
	s_nop 0
	s_nop 1
	v_cmp_gt_f32_e32 vcc, s54, v43
	v_mul_f32_e32 v67, 0x3f317217, v46
	v_pk_add_f32 v[46:47], v[42:43], 1.0 op_sel_hi:[1,0] neg_lo:[1,0] neg_hi:[1,0]
	v_log_f32_e32 v42, v43
	v_pk_add_f32 v[62:63], v[74:75], v[66:67]
	s_nop 1
	v_cmp_gt_f32_e32 vcc, s54, v49
	v_mul_f32_e32 v71, 0x3f317217, v42
	v_pk_add_f32 v[42:43], v[48:49], 1.0 op_sel_hi:[1,0] neg_lo:[1,0] neg_hi:[1,0]
	v_log_f32_e32 v48, v49
	v_pk_add_f32 v[66:67], v[62:63], v[70:71]
	v_add_u32_e32 v70, s33, v122
	s_nop 1
	v_mul_f32_e32 v73, 0x3f317217, v48
	v_pk_add_f32 v[48:49], v[66:67], v[72:73]
	ds_write_b64 v70, v[48:49]
	s_waitcnt vmcnt(1)
	ds_write_b128 v1, v[50:53] offset:32768
	s_waitcnt vmcnt(0)
	ds_write_b128 v149, v[54:57] offset:32768
	s_waitcnt lgkmcnt(0)
	s_barrier
	ds_read2st64_b64 v[70:73], v122 offset1:1
	s_andn2_b64 vcc, exec, s[62:63]
	s_waitcnt lgkmcnt(0)
	v_add_f32_e32 v70, 0, v70
	v_add_f32_e32 v71, 0, v71
	v_cndmask_b32_e64 v94, v71, 0, s[62:63]
	v_cndmask_b32_e64 v95, v70, 0, s[62:63]
	v_add_f32_e32 v96, v70, v72
	v_add_f32_e32 v97, v71, v73
	v_add_f32_e32 v70, v72, v95
	v_add_f32_e32 v71, v73, v94
	v_cndmask_b32_e64 v94, v94, v71, s[4:5]
	v_cndmask_b32_e64 v95, v95, v70, s[4:5]
	ds_read2st64_b64 v[70:73], v122 offset0:2 offset1:3
	s_waitcnt lgkmcnt(0)
	v_add_f32_e32 v96, v96, v70
	v_add_f32_e32 v97, v97, v71
	v_add_f32_e32 v70, v70, v95
	v_add_f32_e32 v71, v71, v94
	v_cndmask_b32_e64 v71, v94, v71, s[6:7]
	v_cndmask_b32_e64 v70, v95, v70, s[6:7]
	v_add_f32_e32 v94, v96, v72
	v_add_f32_e32 v95, v97, v73
	v_add_f32_e32 v72, v72, v70
	v_add_f32_e32 v73, v73, v71
	v_cndmask_b32_e64 v96, v71, v73, s[8:9]
	v_cndmask_b32_e64 v97, v70, v72, s[8:9]
	ds_read2st64_b64 v[70:73], v122 offset0:4 offset1:5
	s_waitcnt lgkmcnt(0)
	v_add_f32_e32 v94, v94, v70
	v_add_f32_e32 v95, v95, v71
	v_add_f32_e32 v70, v70, v97
	v_add_f32_e32 v71, v71, v96
	v_cndmask_b32_e64 v71, v96, v71, s[10:11]
	v_cndmask_b32_e64 v70, v97, v70, s[10:11]
	v_add_f32_e32 v94, v94, v72
	v_add_f32_e32 v95, v95, v73
	v_add_f32_e32 v72, v72, v70
	v_add_f32_e32 v73, v73, v71
	v_cndmask_b32_e64 v96, v71, v73, s[12:13]
	v_cndmask_b32_e64 v97, v70, v72, s[12:13]
	ds_read2st64_b64 v[70:73], v122 offset0:6 offset1:7
	s_waitcnt lgkmcnt(0)
; __device__ __forceinline__ unsigned f2bf(float f) { unsigned u = __float_as_uint(f); return (u + 0x7fffu + ((u >> 16) & 1u)) >> 16; }
; __device__ __forceinline__ unsigned cvtpk(float lo, float hi) { unsigned r; asm volatile("v_cvt_pk_bf16_f32 %0, %1, %2" : "=v"(r) : "v"(lo), "v"(hi)); return r; }
; __device__ __forceinline__ void hg_mfma(Frame& F, bf16* Y, int u, unsigned* prog = nullptr) {
;     ...
;         for (int s = 0; s < 8; ++s) { const v2f x = *(const v2f*)(cs + s * 128 + 2 * dp); tot0 += x.x; tot1 += x.y; if (s < te) { off0 += x.x; off1 += x.y; } }
;         unsigned kh0[4], kh1[4]; const float et0 = __expf(tot0), et1 = __expf(tot1);
; #pragma unroll
;         for (int i = 0; i < 8; ++i) { const float b0 = off0 + c0[i], b1 = off1 + c1[i]; const int t = 8 * te + i;
;           const float e0 = __expf(b0), e1 = __expf(b1), r0 = __builtin_amdgcn_rcpf(e0), r1 = __builtin_amdgcn_rcpf(e1);
;           *(unsigned*)(lds + HG_Q + KSWZ(t, 4 * dp)) = at::cvtpk(q0[i] * e0, q1[i] * e1);
;           const float kt0 = k0[i] * r0, kt1 = k1[i] * r1;
;           *(unsigned*)(lds + HG_K + KSWZ(t, 4 * dp)) = at::cvtpk(kt0, kt1);
;           const float h0 = kt0 * et0, h1 = kt1 * et1;
;           if (i & 1) { kh0[i >> 1] |= f2bf(h0) << 16; kh1[i >> 1] |= f2bf(h1) << 16; } else { kh0[i >> 1] = f2bf(h0); kh1[i >> 1] = f2bf(h1); } }
;         { v4u w; w.x = kh0[0]; w.y = kh0[1]; w.z = kh0[2]; w.w = kh0[3]; *(v4u*)(lds + HG_KH + (2 * dp) * 144 + te * 16) = w;
;           w.x = kh1[0]; w.y = kh1[1]; w.z = kh1[2]; w.w = kh1[3]; *(v4u*)(lds + HG_KH + (2 * dp + 1) * 144 + te * 16) = w; }
;         if (te == 0) { float* dec = (float*)(lds + HG_DEC); dec[2 * dp] = et0; dec[2 * dp + 1] = et1; } }
	v_add_f32_e32 v94, v94, v70
	v_add_f32_e32 v95, v95, v71
	v_add_f32_e32 v70, v70, v97
	v_add_f32_e32 v71, v71, v96
	v_cndmask_b32_e64 v71, v96, v71, s[14:15]
	v_cndmask_b32_e64 v70, v97, v70, s[14:15]
	v_add_f32_e32 v94, v94, v72
	v_add_f32_e32 v95, v95, v73
	v_add_f32_e32 v72, v72, v70
	v_add_f32_e32 v73, v73, v71
	v_cndmask_b32_e64 v71, v71, v73, s[16:17]
	v_cndmask_b32_e64 v73, v70, v72, s[16:17]
	v_add_f32_e32 v76, v76, v73
	v_add_f32_e32 v77, v77, v71
	v_mul_f32_e32 v76, 0x3fb8aa3b, v76
	v_mul_f32_e32 v72, 0x3fb8aa3b, v95
	v_exp_f32_e32 v95, v76
	v_mul_f32_e32 v76, 0x3fb8aa3b, v77
	v_exp_f32_e32 v77, v76
	v_add_f32_e32 v68, v68, v73
	v_mul_f32_e32 v70, 0x3fb8aa3b, v94
	v_mul_f32_e32 v80, v80, v95
	v_rcp_f32_e32 v94, v77
	v_mul_f32_e32 v77, v83, v77
	v_mul_f32_e32 v68, 0x3fb8aa3b, v68
	v_cvt_pk_bf16_f32 v77, v80, v77
	v_exp_f32_e32 v80, v68
	v_rcp_f32_e32 v76, v95
	ds_write_b32 v150, v77
	v_add_f32_e32 v68, v69, v71
	v_rcp_f32_e32 v77, v80
	v_mul_f32_e32 v68, 0x3fb8aa3b, v68
	v_add_f32_e32 v64, v64, v73
	v_add_f32_e32 v65, v65, v71
	v_pk_mul_f32 v[40:41], v[40:41], v[76:77]
	v_exp_f32_e32 v76, v68
	v_mul_f32_e32 v64, 0x3fb8aa3b, v64
	v_exp_f32_e32 v69, v64
	v_mul_f32_e32 v64, 0x3fb8aa3b, v65
	v_rcp_f32_e32 v95, v76
	v_exp_f32_e32 v65, v64
	v_add_f32_e32 v60, v60, v73
	v_mul_f32_e32 v60, 0x3fb8aa3b, v60
	v_exp_f32_e32 v60, v60
	v_pk_mul_f32 v[58:59], v[58:59], v[94:95]
	v_rcp_f32_e32 v64, v69
	v_cvt_pk_bf16_f32 v68, v40, v58
	ds_write_b32 v150, v68 offset:16384
	v_rcp_f32_e32 v68, v65
	v_mul_f32_e32 v65, v81, v65
	v_mul_f32_e32 v69, v78, v69
	v_cvt_pk_bf16_f32 v65, v69, v65
	ds_write_b32 v151, v65 offset:256
	v_rcp_f32_e32 v65, v60
	v_exp_f32_e32 v70, v70
	v_exp_f32_e32 v72, v72
	v_add_f32_e32 v48, v48, v73
	v_pk_mul_f32 v[64:65], v[36:37], v[64:65]
	v_add_f32_e32 v36, v61, v71
	v_mul_f32_e32 v36, 0x3fb8aa3b, v36
	v_exp_f32_e32 v61, v36
	v_mul_f32_e32 v37, v82, v76
	v_add_f32_e32 v49, v49, v71
	v_mul_f32_e32 v48, 0x3fb8aa3b, v48
	v_rcp_f32_e32 v69, v61
	v_mul_f32_e32 v49, 0x3fb8aa3b, v49
	v_exp_f32_e32 v48, v48
	v_exp_f32_e32 v49, v49
	v_pk_mul_f32 v[44:45], v[44:45], v[68:69]
	s_nop 0
	v_cvt_pk_bf16_f32 v36, v64, v44
	ds_write_b32 v151, v36 offset:16640
	v_mul_f32_e32 v36, v79, v80
	v_cvt_pk_bf16_f32 v36, v36, v37
	ds_write_b32 v152, v36 offset:512
	v_cvt_pk_bf16_f32 v36, v41, v59
	ds_write_b32 v152, v36 offset:16896
	v_pk_mul_f32 v[36:37], v[72:73], v[58:59] op_sel_hi:[0,1]
	v_pk_mul_f32 v[58:59], v[70:71], v[40:41] op_sel_hi:[0,1]
	v_mul_f32_e32 v40, v84, v60
	v_mul_f32_e32 v41, v87, v61
	v_cvt_pk_bf16_f32 v40, v40, v41
	v_add_f32_e32 v60, v74, v73
	ds_write_b32 v153, v40 offset:768
	v_cvt_pk_bf16_f32 v40, v65, v45
	v_add_f32_e32 v61, v75, v71
	v_mul_f32_e32 v60, 0x3fb8aa3b, v60
	ds_write_b32 v153, v40 offset:17152
	v_pk_mul_f32 v[40:41], v[72:73], v[44:45] op_sel_hi:[0,1]
	v_pk_mul_f32 v[44:45], v[70:71], v[64:65] op_sel_hi:[0,1]
	v_exp_f32_e32 v65, v60
	v_mul_f32_e32 v60, 0x3fb8aa3b, v61
	v_exp_f32_e32 v61, v60
	v_rcp_f32_e32 v60, v65
	v_mul_f32_e32 v65, v88, v65
	v_rcp_f32_e32 v64, v61
	v_mul_f32_e32 v61, v91, v61
	v_cvt_pk_bf16_f32 v61, v65, v61
	ds_write_b32 v154, v61 offset:1024
	v_add_f32_e32 v61, v66, v73
	v_mul_f32_e32 v61, 0x3fb8aa3b, v61
	v_exp_f32_e32 v66, v61
	v_rcp_f32_e32 v61, v66
	s_nop 0
	v_pk_mul_f32 v[38:39], v[38:39], v[60:61]
	v_add_f32_e32 v60, v67, v71
	v_mul_f32_e32 v60, 0x3fb8aa3b, v60
	v_exp_f32_e32 v67, v60
	v_add_f32_e32 v61, v63, v71
	v_rcp_f32_e32 v65, v67
	s_nop 0
	v_pk_mul_f32 v[46:47], v[46:47], v[64:65]
	s_nop 0
	v_cvt_pk_bf16_f32 v60, v38, v46
	ds_write_b32 v154, v60 offset:17408
	v_add_f32_e32 v60, v62, v73
	v_mul_f32_e32 v60, 0x3fb8aa3b, v60
	v_exp_f32_e32 v63, v60
	v_mul_f32_e32 v60, 0x3fb8aa3b, v61
	v_exp_f32_e32 v61, v60
	v_rcp_f32_e32 v60, v63
	v_mul_f32_e32 v63, v85, v63
	v_rcp_f32_e32 v62, v61
	v_mul_f32_e32 v61, v89, v61
	v_cvt_pk_bf16_f32 v61, v63, v61
	ds_write_b32 v155, v61 offset:1280
	v_rcp_f32_e32 v61, v48
	v_rcp_f32_e32 v63, v49
	v_mul_f32_e32 v48, v92, v48
	v_mul_f32_e32 v49, v93, v49
	v_pk_mul_f32 v[34:35], v[34:35], v[60:61]
	v_pk_mul_f32 v[42:43], v[42:43], v[62:63]
	v_mul_f32_e32 v61, v90, v67
	v_cvt_pk_bf16_f32 v60, v34, v42
	ds_write_b32 v155, v60 offset:17664
	v_mul_f32_e32 v60, v86, v66
	v_cvt_pk_bf16_f32 v60, v60, v61
	ds_write_b32 v156, v60 offset:1536
	v_cvt_pk_bf16_f32 v60, v39, v47
	ds_write_b32 v156, v60 offset:17920
	v_cvt_pk_bf16_f32 v48, v48, v49
	v_pk_mul_f32 v[38:39], v[70:71], v[38:39] op_sel_hi:[0,1]
	ds_write_b32 v157, v48 offset:1792
	v_cvt_pk_bf16_f32 v48, v35, v43
	ds_write_b32 v157, v48 offset:18176
	v_pk_mul_f32 v[48:49], v[72:73], v[42:43] op_sel_hi:[0,1]
	v_pk_mul_f32 v[34:35], v[70:71], v[34:35] op_sel_hi:[0,1]
	v_bfe_u32 v42, v58, 16, 1
	v_bfe_u32 v43, v59, 16, 1
	v_bfe_u32 v60, v38, 16, 1
	v_bfe_u32 v61, v39, 16, 1
	v_add3_u32 v39, v39, v61, s57
	v_add3_u32 v38, v38, v60, s57
	v_add3_u32 v43, v59, v43, s57
	v_add3_u32 v42, v58, v42, s57
	v_bfe_u32 v58, v35, 16, 1
	v_bfe_u32 v59, v34, 16, 1
	v_pk_mul_f32 v[46:47], v[72:73], v[46:47] op_sel_hi:[0,1]
	v_lshrrev_b32_e32 v38, 16, v38
	v_lshrrev_b32_e32 v39, 16, v39
	v_bfe_u32 v60, v45, 16, 1
	v_bfe_u32 v61, v44, 16, 1
	v_add3_u32 v34, v34, v59, s57
	v_add3_u32 v35, v35, v58, s57
	v_lshrrev_b32_e32 v42, 16, v42
	v_lshrrev_b32_e32 v43, 16, v43
	v_add3_u32 v61, v44, v61, s57
	v_add3_u32 v60, v45, v60, s57
	v_and_or_b32 v45, v35, s0, v39
	v_and_or_b32 v44, v34, s0, v38
	v_bfe_u32 v38, v46, 16, 1
	v_bfe_u32 v39, v47, 16, 1
	v_and_or_b32 v43, v60, s0, v43
	v_and_or_b32 v42, v61, s0, v42
	v_bfe_u32 v34, v36, 16, 1
	v_bfe_u32 v35, v37, 16, 1
	v_add3_u32 v39, v47, v39, s57
	v_add3_u32 v38, v46, v38, s57
	ds_write_b128 v158, v[42:45] offset:49152
	v_add3_u32 v35, v37, v35, s57
	v_add3_u32 v34, v36, v34, s57
	v_lshrrev_b32_e32 v36, 16, v38
	v_lshrrev_b32_e32 v37, 16, v39
	v_bfe_u32 v38, v49, 16, 1
	v_bfe_u32 v39, v48, 16, 1
	v_bfe_u32 v42, v41, 16, 1
	v_bfe_u32 v43, v40, 16, 1
	v_lshrrev_b32_e32 v34, 16, v34
	v_lshrrev_b32_e32 v35, 16, v35
	v_add3_u32 v40, v40, v43, s57
	v_add3_u32 v41, v41, v42, s57
	v_add3_u32 v39, v48, v39, s57
	v_add3_u32 v38, v49, v38, s57
	v_and_or_b32 v37, v38, s0, v37
	v_and_or_b32 v36, v39, s0, v36
	v_and_or_b32 v35, v41, s0, v35
	v_and_or_b32 v34, v40, s0, v34
	ds_write_b128 v159, v[34:37] offset:49152
	s_cbranch_vccnz .LBB0_1787
	v_mov_b32_e32 v71, v72
	ds_write_b64 v123, v[70:71]
